# down-GEMM gated-residual epilogue: residual loads pipelined 8 deep (no norm fast path)
# speedup vs baseline: 1.0032x; 1.0032x over previous
.LBB0_1167:
	s_lshl_b64 s[4:5], s[4:5], 2
	v_lshl_or_b32 v158, s9, 8, v168
	s_add_u32 s4, s70, s4
	s_addc_u32 s5, s71, s5
	v_ashrrev_i32_e32 v159, 31, v158
	v_lshl_add_u64 v[66:67], v[158:159], 2, s[4:5]
	s_mov_b64 s[4:5], 0x194ea000
	v_lshl_add_u64 v[68:69], v[66:67], 0, s[4:5]
	s_mov_b32 s4, 0x194ea000
	v_add_co_u32_e32 v66, vcc, s4, v66
	global_load_dwordx4 v[82:85], v[68:69], off offset:16
	s_nop 0
	v_addc_co_u32_e32 v67, vcc, 0, v67, vcc
	global_load_dwordx4 v[86:89], v[66:67], off
	global_load_dwordx4 v[70:73], v[68:69], off offset:512
	s_nop 0
	global_load_dwordx4 v[66:69], v[68:69], off offset:528
	v_lshl_add_u32 v160, s8, 8, v166
	v_ashrrev_i32_e32 v161, 31, v160
	v_lshlrev_b64 v[162:163], 11, v[160:161]
	v_lshl_add_u64 v[162:163], v[162:163], 0, v[158:159]
	s_mov_b64 s[4:5], -1
	s_and_b64 vcc, exec, s[56:57]
	v_lshl_add_u64 v[162:163], v[162:163], 1, s[42:43]
	s_cbranch_vccz .Lepi_down_orig
	v_lshl_add_u32 v162, v160, 11, v158
	v_lshlrev_b32_e32 v162, 1, v162
	s_mov_b64 s[100:101], s[42:43]
	global_load_dwordx4 v[178:181], v162, s[100:101]
	global_load_dwordx4 v[182:185], v162, s[100:101] offset:256
	s_add_u32 s100, s100, 0x10000
	s_addc_u32 s101, s101, 0
	global_load_dwordx4 v[186:189], v162, s[100:101]
	global_load_dwordx4 v[190:193], v162, s[100:101] offset:256
	s_add_u32 s100, s100, 0x10000
	s_addc_u32 s101, s101, 0
	global_load_dwordx4 v[194:197], v162, s[100:101]
	global_load_dwordx4 v[208:211], v162, s[100:101] offset:256
	s_add_u32 s100, s100, 0x10000
	s_addc_u32 s101, s101, 0
	global_load_dwordx4 v[212:215], v162, s[100:101]
	global_load_dwordx4 v[216:219], v162, s[100:101] offset:256
	s_mov_b64 s[100:101], s[42:43]
	s_add_u32 s4, s42, 0x80000
	s_addc_u32 s5, s43, 0
	s_waitcnt vmcnt(7)
	v_pk_mul_f32 v[144:145], v[144:145], v[86:87]
	v_pk_mul_f32 v[146:147], v[146:147], v[88:89]
	v_pk_mul_f32 v[140:141], v[140:141], v[82:83]
	v_pk_mul_f32 v[142:143], v[142:143], v[84:85]
	v_lshlrev_b32_e32 v158, 16, v178
	v_and_b32_e32 v159, 0xffff0000, v178
	v_lshlrev_b32_e32 v160, 16, v179
	v_and_b32_e32 v161, 0xffff0000, v179
	v_pk_add_f32 v[144:145], v[144:145], v[158:159]
	v_pk_add_f32 v[146:147], v[146:147], v[160:161]
	v_lshlrev_b32_e32 v158, 16, v180
	v_and_b32_e32 v159, 0xffff0000, v180
	v_lshlrev_b32_e32 v160, 16, v181
	v_and_b32_e32 v161, 0xffff0000, v181
	v_pk_add_f32 v[140:141], v[140:141], v[158:159]
	v_pk_add_f32 v[142:143], v[142:143], v[160:161]
	v_cvt_pk_bf16_f32 v178, v144, v145
	v_cvt_pk_bf16_f32 v179, v146, v147
	v_cvt_pk_bf16_f32 v180, v140, v141
	v_cvt_pk_bf16_f32 v181, v142, v143
	global_store_dwordx4 v162, v[178:181], s[100:101]
	s_nop 0
	global_load_dwordx4 v[178:181], v162, s[4:5]
	s_waitcnt vmcnt(8)
	v_pk_mul_f32 v[136:137], v[136:137], v[70:71]
	v_pk_mul_f32 v[138:139], v[138:139], v[72:73]
	v_pk_mul_f32 v[132:133], v[132:133], v[66:67]
	v_pk_mul_f32 v[134:135], v[134:135], v[68:69]
	v_lshlrev_b32_e32 v158, 16, v182
	v_and_b32_e32 v159, 0xffff0000, v182
	v_lshlrev_b32_e32 v160, 16, v183
	v_and_b32_e32 v161, 0xffff0000, v183
	v_pk_add_f32 v[136:137], v[136:137], v[158:159]
	v_pk_add_f32 v[138:139], v[138:139], v[160:161]
	v_lshlrev_b32_e32 v158, 16, v184
	v_and_b32_e32 v159, 0xffff0000, v184
	v_lshlrev_b32_e32 v160, 16, v185
	v_and_b32_e32 v161, 0xffff0000, v185
	v_pk_add_f32 v[132:133], v[132:133], v[158:159]
	v_pk_add_f32 v[134:135], v[134:135], v[160:161]
	v_cvt_pk_bf16_f32 v182, v136, v137
	v_cvt_pk_bf16_f32 v183, v138, v139
	v_cvt_pk_bf16_f32 v184, v132, v133
	v_cvt_pk_bf16_f32 v185, v134, v135
	global_store_dwordx4 v162, v[182:185], s[100:101] offset:256
	s_add_u32 s100, s100, 0x10000
	s_addc_u32 s101, s101, 0
	global_load_dwordx4 v[182:185], v162, s[4:5] offset:256
	s_add_u32 s4, s4, 0x10000
	s_addc_u32 s5, s5, 0
	s_waitcnt vmcnt(9)
	v_pk_mul_f32 v[128:129], v[128:129], v[86:87]
	v_pk_mul_f32 v[130:131], v[130:131], v[88:89]
	v_pk_mul_f32 v[124:125], v[124:125], v[82:83]
	v_pk_mul_f32 v[126:127], v[126:127], v[84:85]
	v_lshlrev_b32_e32 v158, 16, v186
	v_and_b32_e32 v159, 0xffff0000, v186
	v_lshlrev_b32_e32 v160, 16, v187
	v_and_b32_e32 v161, 0xffff0000, v187
	v_pk_add_f32 v[128:129], v[128:129], v[158:159]
	v_pk_add_f32 v[130:131], v[130:131], v[160:161]
	v_lshlrev_b32_e32 v158, 16, v188
	v_and_b32_e32 v159, 0xffff0000, v188
	v_lshlrev_b32_e32 v160, 16, v189
	v_and_b32_e32 v161, 0xffff0000, v189
	v_pk_add_f32 v[124:125], v[124:125], v[158:159]
	v_pk_add_f32 v[126:127], v[126:127], v[160:161]
	v_cvt_pk_bf16_f32 v186, v128, v129
	v_cvt_pk_bf16_f32 v187, v130, v131
	v_cvt_pk_bf16_f32 v188, v124, v125
	v_cvt_pk_bf16_f32 v189, v126, v127
	global_store_dwordx4 v162, v[186:189], s[100:101]
	s_nop 0
	global_load_dwordx4 v[186:189], v162, s[4:5]
	s_waitcnt vmcnt(10)
	v_pk_mul_f32 v[120:121], v[120:121], v[70:71]
	v_pk_mul_f32 v[122:123], v[122:123], v[72:73]
	v_pk_mul_f32 v[116:117], v[116:117], v[66:67]
	v_pk_mul_f32 v[118:119], v[118:119], v[68:69]
	v_lshlrev_b32_e32 v158, 16, v190
	v_and_b32_e32 v159, 0xffff0000, v190
	v_lshlrev_b32_e32 v160, 16, v191
	v_and_b32_e32 v161, 0xffff0000, v191
	v_pk_add_f32 v[120:121], v[120:121], v[158:159]
	v_pk_add_f32 v[122:123], v[122:123], v[160:161]
	v_lshlrev_b32_e32 v158, 16, v192
	v_and_b32_e32 v159, 0xffff0000, v192
	v_lshlrev_b32_e32 v160, 16, v193
	v_and_b32_e32 v161, 0xffff0000, v193
	v_pk_add_f32 v[116:117], v[116:117], v[158:159]
	v_pk_add_f32 v[118:119], v[118:119], v[160:161]
	v_cvt_pk_bf16_f32 v190, v120, v121
	v_cvt_pk_bf16_f32 v191, v122, v123
	v_cvt_pk_bf16_f32 v192, v116, v117
	v_cvt_pk_bf16_f32 v193, v118, v119
	global_store_dwordx4 v162, v[190:193], s[100:101] offset:256
	s_add_u32 s100, s100, 0x10000
	s_addc_u32 s101, s101, 0
	global_load_dwordx4 v[190:193], v162, s[4:5] offset:256
	s_add_u32 s4, s4, 0x10000
	s_addc_u32 s5, s5, 0
	s_waitcnt vmcnt(11)
	v_pk_mul_f32 v[112:113], v[112:113], v[86:87]
	v_pk_mul_f32 v[114:115], v[114:115], v[88:89]
	v_pk_mul_f32 v[108:109], v[108:109], v[82:83]
	v_pk_mul_f32 v[110:111], v[110:111], v[84:85]
	v_lshlrev_b32_e32 v158, 16, v194
	v_and_b32_e32 v159, 0xffff0000, v194
	v_lshlrev_b32_e32 v160, 16, v195
	v_and_b32_e32 v161, 0xffff0000, v195
	v_pk_add_f32 v[112:113], v[112:113], v[158:159]
	v_pk_add_f32 v[114:115], v[114:115], v[160:161]
	v_lshlrev_b32_e32 v158, 16, v196
	v_and_b32_e32 v159, 0xffff0000, v196
	v_lshlrev_b32_e32 v160, 16, v197
	v_and_b32_e32 v161, 0xffff0000, v197
	v_pk_add_f32 v[108:109], v[108:109], v[158:159]
	v_pk_add_f32 v[110:111], v[110:111], v[160:161]
	v_cvt_pk_bf16_f32 v194, v112, v113
	v_cvt_pk_bf16_f32 v195, v114, v115
	v_cvt_pk_bf16_f32 v196, v108, v109
	v_cvt_pk_bf16_f32 v197, v110, v111
	global_store_dwordx4 v162, v[194:197], s[100:101]
	s_nop 0
	global_load_dwordx4 v[194:197], v162, s[4:5]
	s_waitcnt vmcnt(12)
	v_pk_mul_f32 v[104:105], v[104:105], v[70:71]
	v_pk_mul_f32 v[106:107], v[106:107], v[72:73]
	v_pk_mul_f32 v[100:101], v[100:101], v[66:67]
	v_pk_mul_f32 v[102:103], v[102:103], v[68:69]
	v_lshlrev_b32_e32 v158, 16, v208
	v_and_b32_e32 v159, 0xffff0000, v208
	v_lshlrev_b32_e32 v160, 16, v209
	v_and_b32_e32 v161, 0xffff0000, v209
	v_pk_add_f32 v[104:105], v[104:105], v[158:159]
	v_pk_add_f32 v[106:107], v[106:107], v[160:161]
	v_lshlrev_b32_e32 v158, 16, v210
	v_and_b32_e32 v159, 0xffff0000, v210
	v_lshlrev_b32_e32 v160, 16, v211
	v_and_b32_e32 v161, 0xffff0000, v211
	v_pk_add_f32 v[100:101], v[100:101], v[158:159]
	v_pk_add_f32 v[102:103], v[102:103], v[160:161]
	v_cvt_pk_bf16_f32 v208, v104, v105
	v_cvt_pk_bf16_f32 v209, v106, v107
	v_cvt_pk_bf16_f32 v210, v100, v101
	v_cvt_pk_bf16_f32 v211, v102, v103
	global_store_dwordx4 v162, v[208:211], s[100:101] offset:256
	s_add_u32 s100, s100, 0x10000
	s_addc_u32 s101, s101, 0
	global_load_dwordx4 v[208:211], v162, s[4:5] offset:256
	s_add_u32 s4, s4, 0x10000
	s_addc_u32 s5, s5, 0
	s_waitcnt vmcnt(13)
	v_pk_mul_f32 v[94:95], v[94:95], v[86:87]
	v_pk_mul_f32 v[96:97], v[96:97], v[88:89]
	v_pk_mul_f32 v[90:91], v[90:91], v[82:83]
	v_pk_mul_f32 v[92:93], v[92:93], v[84:85]
	v_lshlrev_b32_e32 v158, 16, v212
	v_and_b32_e32 v159, 0xffff0000, v212
	v_lshlrev_b32_e32 v160, 16, v213
	v_and_b32_e32 v161, 0xffff0000, v213
	v_pk_add_f32 v[94:95], v[94:95], v[158:159]
	v_pk_add_f32 v[96:97], v[96:97], v[160:161]
	v_lshlrev_b32_e32 v158, 16, v214
	v_and_b32_e32 v159, 0xffff0000, v214
	v_lshlrev_b32_e32 v160, 16, v215
	v_and_b32_e32 v161, 0xffff0000, v215
	v_pk_add_f32 v[90:91], v[90:91], v[158:159]
	v_pk_add_f32 v[92:93], v[92:93], v[160:161]
	v_cvt_pk_bf16_f32 v212, v94, v95
	v_cvt_pk_bf16_f32 v213, v96, v97
	v_cvt_pk_bf16_f32 v214, v90, v91
	v_cvt_pk_bf16_f32 v215, v92, v93
	global_store_dwordx4 v162, v[212:215], s[100:101]
	s_nop 0
	global_load_dwordx4 v[212:215], v162, s[4:5]
	s_waitcnt vmcnt(14)
	v_pk_mul_f32 v[78:79], v[78:79], v[70:71]
	v_pk_mul_f32 v[80:81], v[80:81], v[72:73]
	v_pk_mul_f32 v[74:75], v[74:75], v[66:67]
	v_pk_mul_f32 v[76:77], v[76:77], v[68:69]
	v_lshlrev_b32_e32 v158, 16, v216
	v_and_b32_e32 v159, 0xffff0000, v216
	v_lshlrev_b32_e32 v160, 16, v217
	v_and_b32_e32 v161, 0xffff0000, v217
	v_pk_add_f32 v[78:79], v[78:79], v[158:159]
	v_pk_add_f32 v[80:81], v[80:81], v[160:161]
	v_lshlrev_b32_e32 v158, 16, v218
	v_and_b32_e32 v159, 0xffff0000, v218
	v_lshlrev_b32_e32 v160, 16, v219
	v_and_b32_e32 v161, 0xffff0000, v219
	v_pk_add_f32 v[74:75], v[74:75], v[158:159]
	v_pk_add_f32 v[76:77], v[76:77], v[160:161]
	v_cvt_pk_bf16_f32 v216, v78, v79
	v_cvt_pk_bf16_f32 v217, v80, v81
	v_cvt_pk_bf16_f32 v218, v74, v75
	v_cvt_pk_bf16_f32 v219, v76, v77
	global_store_dwordx4 v162, v[216:219], s[100:101] offset:256
	s_add_u32 s100, s100, 0x10000
	s_addc_u32 s101, s101, 0
	global_load_dwordx4 v[216:219], v162, s[4:5] offset:256
	s_add_u32 s4, s42, 0x80000
	s_addc_u32 s5, s43, 0
	s_waitcnt vmcnt(14)
	v_pk_mul_f32 v[62:63], v[62:63], v[86:87]
	v_pk_mul_f32 v[64:65], v[64:65], v[88:89]
	v_pk_mul_f32 v[58:59], v[58:59], v[82:83]
	v_pk_mul_f32 v[60:61], v[60:61], v[84:85]
	v_lshlrev_b32_e32 v158, 16, v178
	v_and_b32_e32 v159, 0xffff0000, v178
	v_lshlrev_b32_e32 v160, 16, v179
	v_and_b32_e32 v161, 0xffff0000, v179
	v_pk_add_f32 v[62:63], v[62:63], v[158:159]
	v_pk_add_f32 v[64:65], v[64:65], v[160:161]
	v_lshlrev_b32_e32 v158, 16, v180
	v_and_b32_e32 v159, 0xffff0000, v180
	v_lshlrev_b32_e32 v160, 16, v181
	v_and_b32_e32 v161, 0xffff0000, v181
	v_pk_add_f32 v[58:59], v[58:59], v[158:159]
	v_pk_add_f32 v[60:61], v[60:61], v[160:161]
	v_cvt_pk_bf16_f32 v178, v62, v63
	v_cvt_pk_bf16_f32 v179, v64, v65
	v_cvt_pk_bf16_f32 v180, v58, v59
	v_cvt_pk_bf16_f32 v181, v60, v61
	global_store_dwordx4 v162, v[178:181], s[4:5]
	s_waitcnt vmcnt(13)
	v_pk_mul_f32 v[54:55], v[54:55], v[70:71]
	v_pk_mul_f32 v[56:57], v[56:57], v[72:73]
	v_pk_mul_f32 v[50:51], v[50:51], v[66:67]
	v_pk_mul_f32 v[52:53], v[52:53], v[68:69]
	v_lshlrev_b32_e32 v158, 16, v182
	v_and_b32_e32 v159, 0xffff0000, v182
	v_lshlrev_b32_e32 v160, 16, v183
	v_and_b32_e32 v161, 0xffff0000, v183
	v_pk_add_f32 v[54:55], v[54:55], v[158:159]
	v_pk_add_f32 v[56:57], v[56:57], v[160:161]
	v_lshlrev_b32_e32 v158, 16, v184
	v_and_b32_e32 v159, 0xffff0000, v184
	v_lshlrev_b32_e32 v160, 16, v185
	v_and_b32_e32 v161, 0xffff0000, v185
	v_pk_add_f32 v[50:51], v[50:51], v[158:159]
	v_pk_add_f32 v[52:53], v[52:53], v[160:161]
	v_cvt_pk_bf16_f32 v182, v54, v55
	v_cvt_pk_bf16_f32 v183, v56, v57
	v_cvt_pk_bf16_f32 v184, v50, v51
	v_cvt_pk_bf16_f32 v185, v52, v53
	global_store_dwordx4 v162, v[182:185], s[4:5] offset:256
	s_add_u32 s4, s4, 0x10000
	s_addc_u32 s5, s5, 0
	s_waitcnt vmcnt(12)
	v_pk_mul_f32 v[46:47], v[46:47], v[86:87]
	v_pk_mul_f32 v[48:49], v[48:49], v[88:89]
	v_pk_mul_f32 v[42:43], v[42:43], v[82:83]
	v_pk_mul_f32 v[44:45], v[44:45], v[84:85]
	v_lshlrev_b32_e32 v158, 16, v186
	v_and_b32_e32 v159, 0xffff0000, v186
	v_lshlrev_b32_e32 v160, 16, v187
	v_and_b32_e32 v161, 0xffff0000, v187
	v_pk_add_f32 v[46:47], v[46:47], v[158:159]
	v_pk_add_f32 v[48:49], v[48:49], v[160:161]
	v_lshlrev_b32_e32 v158, 16, v188
	v_and_b32_e32 v159, 0xffff0000, v188
	v_lshlrev_b32_e32 v160, 16, v189
	v_and_b32_e32 v161, 0xffff0000, v189
	v_pk_add_f32 v[42:43], v[42:43], v[158:159]
	v_pk_add_f32 v[44:45], v[44:45], v[160:161]
	v_cvt_pk_bf16_f32 v186, v46, v47
	v_cvt_pk_bf16_f32 v187, v48, v49
	v_cvt_pk_bf16_f32 v188, v42, v43
	v_cvt_pk_bf16_f32 v189, v44, v45
	global_store_dwordx4 v162, v[186:189], s[4:5]
	s_waitcnt vmcnt(11)
	v_pk_mul_f32 v[38:39], v[38:39], v[70:71]
	v_pk_mul_f32 v[40:41], v[40:41], v[72:73]
	v_pk_mul_f32 v[34:35], v[34:35], v[66:67]
	v_pk_mul_f32 v[36:37], v[36:37], v[68:69]
	v_lshlrev_b32_e32 v158, 16, v190
	v_and_b32_e32 v159, 0xffff0000, v190
	v_lshlrev_b32_e32 v160, 16, v191
	v_and_b32_e32 v161, 0xffff0000, v191
	v_pk_add_f32 v[38:39], v[38:39], v[158:159]
	v_pk_add_f32 v[40:41], v[40:41], v[160:161]
	v_lshlrev_b32_e32 v158, 16, v192
	v_and_b32_e32 v159, 0xffff0000, v192
	v_lshlrev_b32_e32 v160, 16, v193
	v_and_b32_e32 v161, 0xffff0000, v193
	v_pk_add_f32 v[34:35], v[34:35], v[158:159]
	v_pk_add_f32 v[36:37], v[36:37], v[160:161]
	v_cvt_pk_bf16_f32 v190, v38, v39
	v_cvt_pk_bf16_f32 v191, v40, v41
	v_cvt_pk_bf16_f32 v192, v34, v35
	v_cvt_pk_bf16_f32 v193, v36, v37
	global_store_dwordx4 v162, v[190:193], s[4:5] offset:256
	s_add_u32 s4, s4, 0x10000
	s_addc_u32 s5, s5, 0
	s_waitcnt vmcnt(10)
	v_pk_mul_f32 v[30:31], v[30:31], v[86:87]
	v_pk_mul_f32 v[32:33], v[32:33], v[88:89]
	v_pk_mul_f32 v[26:27], v[26:27], v[82:83]
	v_pk_mul_f32 v[28:29], v[28:29], v[84:85]
	v_lshlrev_b32_e32 v158, 16, v194
	v_and_b32_e32 v159, 0xffff0000, v194
	v_lshlrev_b32_e32 v160, 16, v195
	v_and_b32_e32 v161, 0xffff0000, v195
	v_pk_add_f32 v[30:31], v[30:31], v[158:159]
	v_pk_add_f32 v[32:33], v[32:33], v[160:161]
	v_lshlrev_b32_e32 v158, 16, v196
	v_and_b32_e32 v159, 0xffff0000, v196
	v_lshlrev_b32_e32 v160, 16, v197
	v_and_b32_e32 v161, 0xffff0000, v197
	v_pk_add_f32 v[26:27], v[26:27], v[158:159]
	v_pk_add_f32 v[28:29], v[28:29], v[160:161]
	v_cvt_pk_bf16_f32 v194, v30, v31
	v_cvt_pk_bf16_f32 v195, v32, v33
	v_cvt_pk_bf16_f32 v196, v26, v27
	v_cvt_pk_bf16_f32 v197, v28, v29
	global_store_dwordx4 v162, v[194:197], s[4:5]
	s_waitcnt vmcnt(9)
	v_pk_mul_f32 v[22:23], v[22:23], v[70:71]
	v_pk_mul_f32 v[24:25], v[24:25], v[72:73]
	v_pk_mul_f32 v[18:19], v[18:19], v[66:67]
	v_pk_mul_f32 v[20:21], v[20:21], v[68:69]
	v_lshlrev_b32_e32 v158, 16, v208
	v_and_b32_e32 v159, 0xffff0000, v208
	v_lshlrev_b32_e32 v160, 16, v209
	v_and_b32_e32 v161, 0xffff0000, v209
	v_pk_add_f32 v[22:23], v[22:23], v[158:159]
	v_pk_add_f32 v[24:25], v[24:25], v[160:161]
	v_lshlrev_b32_e32 v158, 16, v210
	v_and_b32_e32 v159, 0xffff0000, v210
	v_lshlrev_b32_e32 v160, 16, v211
	v_and_b32_e32 v161, 0xffff0000, v211
	v_pk_add_f32 v[18:19], v[18:19], v[158:159]
	v_pk_add_f32 v[20:21], v[20:21], v[160:161]
	v_cvt_pk_bf16_f32 v208, v22, v23
	v_cvt_pk_bf16_f32 v209, v24, v25
	v_cvt_pk_bf16_f32 v210, v18, v19
	v_cvt_pk_bf16_f32 v211, v20, v21
	global_store_dwordx4 v162, v[208:211], s[4:5] offset:256
	s_add_u32 s4, s4, 0x10000
	s_addc_u32 s5, s5, 0
	s_waitcnt vmcnt(8)
	v_pk_mul_f32 v[14:15], v[14:15], v[86:87]
	v_pk_mul_f32 v[16:17], v[16:17], v[88:89]
	v_pk_mul_f32 v[10:11], v[10:11], v[82:83]
	v_pk_mul_f32 v[12:13], v[12:13], v[84:85]
	v_lshlrev_b32_e32 v158, 16, v212
	v_and_b32_e32 v159, 0xffff0000, v212
	v_lshlrev_b32_e32 v160, 16, v213
	v_and_b32_e32 v161, 0xffff0000, v213
	v_pk_add_f32 v[14:15], v[14:15], v[158:159]
	v_pk_add_f32 v[16:17], v[16:17], v[160:161]
	v_lshlrev_b32_e32 v158, 16, v214
	v_and_b32_e32 v159, 0xffff0000, v214
	v_lshlrev_b32_e32 v160, 16, v215
	v_and_b32_e32 v161, 0xffff0000, v215
	v_pk_add_f32 v[10:11], v[10:11], v[158:159]
	v_pk_add_f32 v[12:13], v[12:13], v[160:161]
	v_cvt_pk_bf16_f32 v212, v14, v15
	v_cvt_pk_bf16_f32 v213, v16, v17
	v_cvt_pk_bf16_f32 v214, v10, v11
	v_cvt_pk_bf16_f32 v215, v12, v13
	global_store_dwordx4 v162, v[212:215], s[4:5]
	s_waitcnt vmcnt(7)
	v_pk_mul_f32 v[6:7], v[6:7], v[70:71]
	v_pk_mul_f32 v[8:9], v[8:9], v[72:73]
	v_pk_mul_f32 v[2:3], v[2:3], v[66:67]
	v_pk_mul_f32 v[4:5], v[4:5], v[68:69]
	v_lshlrev_b32_e32 v158, 16, v216
	v_and_b32_e32 v159, 0xffff0000, v216
	v_lshlrev_b32_e32 v160, 16, v217
	v_and_b32_e32 v161, 0xffff0000, v217
	v_pk_add_f32 v[6:7], v[6:7], v[158:159]
	v_pk_add_f32 v[8:9], v[8:9], v[160:161]
	v_lshlrev_b32_e32 v158, 16, v218
	v_and_b32_e32 v159, 0xffff0000, v218
	v_lshlrev_b32_e32 v160, 16, v219
	v_and_b32_e32 v161, 0xffff0000, v219
	v_pk_add_f32 v[2:3], v[2:3], v[158:159]
	v_pk_add_f32 v[4:5], v[4:5], v[160:161]
	v_cvt_pk_bf16_f32 v216, v6, v7
	v_cvt_pk_bf16_f32 v217, v8, v9
	v_cvt_pk_bf16_f32 v218, v2, v3
	v_cvt_pk_bf16_f32 v219, v4, v5
	global_store_dwordx4 v162, v[216:219], s[4:5] offset:256
	s_branch .LBB0_1229
.Lepi_down_orig:
	s_waitcnt vmcnt(0)
	v_pk_mul_f32 v[142:143], v[142:143], v[84:85]
	v_pk_mul_f32 v[140:141], v[140:141], v[82:83]
	v_pk_mul_f32 v[146:147], v[146:147], v[88:89]
	v_pk_mul_f32 v[144:145], v[144:145], v[86:87]
	s_cbranch_vccz .LBB0_1169
	global_load_dwordx4 v[170:173], v[162:163], off
	s_mov_b64 s[4:5], 0
	s_waitcnt vmcnt(0)
	v_lshlrev_b32_e32 v174, 16, v172
	v_and_b32_e32 v175, 0xffff0000, v172
	v_lshlrev_b32_e32 v172, 16, v173
	v_and_b32_e32 v173, 0xffff0000, v173
	v_lshlrev_b32_e32 v164, 16, v170
	v_and_b32_e32 v165, 0xffff0000, v170
	v_lshlrev_b32_e32 v170, 16, v171
	v_and_b32_e32 v171, 0xffff0000, v171
	v_pk_add_f32 v[178:179], v[142:143], v[172:173]
	v_pk_add_f32 v[172:173], v[140:141], v[174:175]
	v_pk_add_f32 v[176:177], v[146:147], v[170:171]
	v_pk_add_f32 v[164:165], v[144:145], v[164:165]
	s_nop 0
	v_cvt_pk_bf16_f32 v170, v164, v165
	v_cvt_pk_bf16_f32 v171, v176, v177
	v_cvt_pk_bf16_f32 v172, v172, v173
	v_cvt_pk_bf16_f32 v173, v178, v179
	global_store_dwordx4 v[162:163], v[170:173], off
